# FFN2-up: row sum-of-squares for the epilogue prefetched in the peeled first K iteration (counted waits adjusted), epilogue no longer waits on them
# baseline (speedup 1.0000x reference)
; #define PG8_STAGE(bufoff, gbase, voff) do { _Pragma("unroll") for (int _i = 0; _i < 2; ++_i) \
;         __builtin_amdgcn_global_load_lds((const unsigned*)((const char*)(gbase) + (voff)[_i]), (PG8_LAS unsigned*)(lds + (bufoff) + ldsw + _i * 8192), 16, 0, 0); } while (0)
; #define PG8_LDA(dst, b, h) do { _Pragma("unroll") for (int m = 0; m < 4; ++m) _Pragma("unroll") for (int k = 0; k < 2; ++k) dst[m][k] = *(const PG8_LAS bf16x8*)(lds + PG8_SA(b, h) + aoff + m * 2048 + k * 1024); } while (0)
; #define PG8_LDB(dst, b, h) do { _Pragma("unroll") for (int n = 0; n < 2; ++n) _Pragma("unroll") for (int k = 0; k < 2; ++k) dst[n][k] = *(const PG8_LAS bf16x8*)(lds + PG8_SB(b, h) + boff + n * 2048 + k * 1024); } while (0)
; #define PG8_MMA(ai, bj, At, Bt) do { __builtin_amdgcn_s_setprio(1); _Pragma("unroll") for (int m = 0; m < 4; ++m) _Pragma("unroll") for (int n = 0; n < 2; ++n) _Pragma("unroll") for (int k = 0; k < 2; ++k) \
;         acc[ai][bj][m][n] = __builtin_amdgcn_mfma_f32_16x16x32_bf16(Bt[n][k], At[m][k], acc[ai][bj][m][n], 0, 0, 0); __builtin_amdgcn_s_setprio(0); } while (0)
; #define PG8_WAIT_V(n) asm volatile("s_waitcnt vmcnt(" #n ")" ::: "memory")
; #define PG8_WAIT_L(n) asm volatile("s_waitcnt lgkmcnt(" #n ")" ::: "memory")
; #define PG8_BAR __builtin_amdgcn_s_barrier()
; #define PG8_SCHED __builtin_amdgcn_sched_barrier(0)
; template <class Epi, class Sched, bool ALIGN_EPI = false, bool SP2 = false, bool ABLK = false>
; __device__ __forceinline__ void gemm_phase(PG8_LAS unsigned char* lds, const Gemm g, const Sched& S, const Epi& E) {
;     ...
;             PG8_LDB(B0, 0, 0); PG8_LDB(B1, 0, 1); PG8_SCHED; PG8_LDA(At, 0, 0); PG8_STAGE(PG8_SA(1, 1), a1 + hstepA, voffA);
;             PG8_WAIT_V(8); PG8_WAIT_L(0); PG8_BAR; PG8_MMA(0, 0, At, B0); PG8_MMA(0, 1, At, B1); PG8_BAR; PG8_SCHED;
;             PG8_LDA(At, 0, 1); PG8_STAGE(PG8_SB(0, 0), b2, voffB); PG8_STAGE(PG8_SB(0, 1), b2 + hstep, voffB); PG8_STAGE(PG8_SA(0, 0), a2, voffA);
;             PG8_WAIT_V(8); PG8_WAIT_L(0); PG8_BAR; PG8_MMA(1, 0, At, B0); PG8_MMA(1, 1, At, B1); PG8_BAR; PG8_SCHED;
;     __device__ __forceinline__ void operator()(const f32x4 (&acc)[2][2][4][2], const pg8::Unit& u, int wr, int wc, int fr, int fq) const {
;     ...
;                 const float r = SCALE ? rstd_of(SS, row, 1.f / 1024.f) : 1.f;
.LBB0_824:
	v_lshl_add_u32 v246, s0, 8, v160
	v_ashrrev_i32_e32 v247, 31, v246
	v_lshl_add_u64 v[246:247], v[246:247], 2, s[44:45]
	global_load_dword v238, v[246:247], off
	global_load_dword v239, v[246:247], off offset:64
	global_load_dword v240, v[246:247], off offset:128
	global_load_dword v241, v[246:247], off offset:192
	global_load_dword v242, v[246:247], off offset:512
	global_load_dword v243, v[246:247], off offset:576
	global_load_dword v244, v[246:247], off offset:640
	global_load_dword v245, v[246:247], off offset:704
	ds_read_b128 v[156:159], v162
	ds_read_b128 v[168:171], v162 offset:1024
	ds_read_b128 v[172:175], v162 offset:2048
	ds_read_b128 v[176:179], v162 offset:3072
	ds_read_b128 v[180:183], v163
	ds_read_b128 v[184:187], v163 offset:1024
	ds_read_b128 v[188:191], v163 offset:2048
	ds_read_b128 v[192:195], v163 offset:3072
	s_add_u32 s11, s36, 0xfffc0080
	s_addc_u32 s14, s37, -1
	s_cmp_eq_u32 s10, 12
	s_cselect_b32 s53, s4, s14
	s_cselect_b32 s52, s5, s11
	s_cselect_b32 s51, s6, s9
	s_cselect_b32 s50, s7, s8
	v_lshl_add_u64 v[228:229], s[36:37], 0, v[148:149]
	s_add_i32 m0, s58, 0xc000
	ds_read_b128 v[196:199], v164
	ds_read_b128 v[200:203], v164 offset:1024
	ds_read_b128 v[204:207], v164 offset:2048
	ds_read_b128 v[208:211], v164 offset:3072
	ds_read_b128 v[212:215], v164 offset:4096
	ds_read_b128 v[216:219], v164 offset:5120
	ds_read_b128 v[220:223], v164 offset:6144
	ds_read_b128 v[224:227], v164 offset:7168
	global_load_lds_dwordx4 v[228:229], off
	v_lshl_add_u64 v[228:229], s[36:37], 0, v[150:151]
	s_add_i32 m0, s58, 0xe000
	s_nop 0
	global_load_lds_dwordx4 v[228:229], off
	s_waitcnt vmcnt(16)
	s_waitcnt lgkmcnt(0)
	s_barrier
	s_setprio 1
	s_waitcnt lgkmcnt(0)
	v_mfma_f32_16x16x32_bf16 v[124:127], v[156:159], v[196:199], 0
	v_mfma_f32_16x16x32_bf16 v[120:123], v[172:175], v[196:199], 0
	v_mfma_f32_16x16x32_bf16 v[108:111], v[156:159], v[204:207], 0
	v_mfma_f32_16x16x32_bf16 v[104:107], v[172:175], v[204:207], 0
	v_mfma_f32_16x16x32_bf16 v[92:95], v[156:159], v[212:215], 0
	v_mfma_f32_16x16x32_bf16 v[88:91], v[172:175], v[212:215], 0
	v_mfma_f32_16x16x32_bf16 v[76:79], v[156:159], v[220:223], 0
	v_mfma_f32_16x16x32_bf16 v[72:75], v[172:175], v[220:223], 0
	v_mfma_f32_16x16x32_bf16 v[124:127], v[168:171], v[200:203], v[124:127]
	v_mfma_f32_16x16x32_bf16 v[120:123], v[176:179], v[200:203], v[120:123]
	v_mfma_f32_16x16x32_bf16 v[108:111], v[168:171], v[208:211], v[108:111]
	v_mfma_f32_16x16x32_bf16 v[104:107], v[176:179], v[208:211], v[104:107]
	v_mfma_f32_16x16x32_bf16 v[92:95], v[168:171], v[216:219], v[92:95]
	v_mfma_f32_16x16x32_bf16 v[88:91], v[176:179], v[216:219], v[88:91]
	v_mfma_f32_16x16x32_bf16 v[76:79], v[168:171], v[224:227], v[76:79]
	v_mfma_f32_16x16x32_bf16 v[72:75], v[176:179], v[224:227], v[72:75]
	s_setprio 0
	s_setprio 1
	v_mfma_f32_16x16x32_bf16 v[116:119], v[180:183], v[196:199], 0
	v_mfma_f32_16x16x32_bf16 v[112:115], v[188:191], v[196:199], 0
	v_mfma_f32_16x16x32_bf16 v[100:103], v[180:183], v[204:207], 0
	v_mfma_f32_16x16x32_bf16 v[96:99], v[188:191], v[204:207], 0
	v_mfma_f32_16x16x32_bf16 v[84:87], v[180:183], v[212:215], 0
	v_mfma_f32_16x16x32_bf16 v[80:83], v[188:191], v[212:215], 0
	v_mfma_f32_16x16x32_bf16 v[68:71], v[180:183], v[220:223], 0
	v_mfma_f32_16x16x32_bf16 v[64:67], v[188:191], v[220:223], 0
	v_mfma_f32_16x16x32_bf16 v[116:119], v[184:187], v[200:203], v[116:119]
	v_mfma_f32_16x16x32_bf16 v[112:115], v[192:195], v[200:203], v[112:115]
	v_mfma_f32_16x16x32_bf16 v[100:103], v[184:187], v[208:211], v[100:103]
	v_mfma_f32_16x16x32_bf16 v[96:99], v[192:195], v[208:211], v[96:99]
	v_mfma_f32_16x16x32_bf16 v[84:87], v[184:187], v[216:219], v[84:87]
	v_mfma_f32_16x16x32_bf16 v[80:83], v[192:195], v[216:219], v[80:83]
	v_mfma_f32_16x16x32_bf16 v[68:71], v[184:187], v[224:227], v[68:71]
	v_mfma_f32_16x16x32_bf16 v[64:67], v[192:195], v[224:227], v[64:67]
	s_setprio 0
	s_barrier
	s_add_i32 s11, s70, s54
	v_lshl_add_u64 v[228:229], s[50:51], 0, v[132:133]
	s_mov_b32 m0, s11
	ds_read_b128 v[196:199], v164 offset:16384
	ds_read_b128 v[200:203], v164 offset:17408
	ds_read_b128 v[204:207], v164 offset:18432
	ds_read_b128 v[208:211], v164 offset:19456
	ds_read_b128 v[212:215], v164 offset:20480
	ds_read_b128 v[216:219], v164 offset:21504
	ds_read_b128 v[220:223], v164 offset:22528
	ds_read_b128 v[224:227], v164 offset:23552
	global_load_lds_dwordx4 v[228:229], off
	s_add_i32 m0, s11, 0x2000
	s_add_u32 s14, s50, 0x40000
	v_lshl_add_u64 v[230:231], s[50:51], 0, v[128:129]
	s_addc_u32 s15, s51, 0
	s_add_i32 s11, s71, s54
	global_load_lds_dwordx4 v[230:231], off
	v_lshl_add_u64 v[232:233], s[14:15], 0, v[132:133]
	s_mov_b32 m0, s11
	v_lshl_add_u64 v[234:235], s[52:53], 0, v[130:131]
	global_load_lds_dwordx4 v[232:233], off
	v_lshl_add_u64 v[232:233], s[14:15], 0, v[128:129]
	s_add_i32 m0, s11, 0x2000
	s_nop 0
	global_load_lds_dwordx4 v[232:233], off
	v_lshl_add_u64 v[232:233], s[52:53], 0, v[134:135]
	s_mov_b32 m0, s58
	s_nop 0
	global_load_lds_dwordx4 v[232:233], off
	s_mov_b32 m0, s59
	s_nop 0
	global_load_lds_dwordx4 v[234:235], off
	s_waitcnt vmcnt(16)
	s_waitcnt lgkmcnt(0)
	s_barrier
; #define PG8_STAGE(bufoff, gbase, voff) do { _Pragma("unroll") for (int _i = 0; _i < 2; ++_i) \
;         __builtin_amdgcn_global_load_lds((const unsigned*)((const char*)(gbase) + (voff)[_i]), (PG8_LAS unsigned*)(lds + (bufoff) + ldsw + _i * 8192), 16, 0, 0); } while (0)
; #define PG8_LDA(dst, b, h) do { _Pragma("unroll") for (int m = 0; m < 4; ++m) _Pragma("unroll") for (int k = 0; k < 2; ++k) dst[m][k] = *(const PG8_LAS bf16x8*)(lds + PG8_SA(b, h) + aoff + m * 2048 + k * 1024); } while (0)
; #define PG8_LDB(dst, b, h) do { _Pragma("unroll") for (int n = 0; n < 2; ++n) _Pragma("unroll") for (int k = 0; k < 2; ++k) dst[n][k] = *(const PG8_LAS bf16x8*)(lds + PG8_SB(b, h) + boff + n * 2048 + k * 1024); } while (0)
; #define PG8_MMA(ai, bj, At, Bt) do { __builtin_amdgcn_s_setprio(1); _Pragma("unroll") for (int m = 0; m < 4; ++m) _Pragma("unroll") for (int n = 0; n < 2; ++n) _Pragma("unroll") for (int k = 0; k < 2; ++k) \
;         acc[ai][bj][m][n] = __builtin_amdgcn_mfma_f32_16x16x32_bf16(Bt[n][k], At[m][k], acc[ai][bj][m][n], 0, 0, 0); __builtin_amdgcn_s_setprio(0); } while (0)
; #define PG8_WAIT_V(n) asm volatile("s_waitcnt vmcnt(" #n ")" ::: "memory")
; #define PG8_WAIT_L(n) asm volatile("s_waitcnt lgkmcnt(" #n ")" ::: "memory")
; #define PG8_BAR __builtin_amdgcn_s_barrier()
; #define PG8_SCHED __builtin_amdgcn_sched_barrier(0)
; template <class Epi, class Sched, bool ALIGN_EPI = false, bool SP2 = false, bool ABLK = false>
; __device__ __forceinline__ void gemm_phase(PG8_LAS unsigned char* lds, const Gemm g, const Sched& S, const Epi& E) {
;     ...
;             PG8_WAIT_V(8); PG8_WAIT_L(0); PG8_BAR; PG8_MMA(1, 0, At, B0); PG8_MMA(1, 1, At, B1); PG8_BAR; PG8_SCHED;
;             PG8_LDB(B0, 1, 0); PG8_LDB(B1, 1, 1); PG8_SCHED; PG8_LDA(At, 1, 0); PG8_STAGE(PG8_SA(0, 1), a2 + hstepA, voffA);
;             PG8_WAIT_V(8); PG8_WAIT_L(0); PG8_BAR; PG8_MMA(0, 0, At, B0); PG8_MMA(0, 1, At, B1); PG8_BAR; PG8_SCHED;
	s_setprio 1
	s_waitcnt lgkmcnt(0)
	v_mfma_f32_16x16x32_bf16 v[60:63], v[156:159], v[196:199], 0
	v_mfma_f32_16x16x32_bf16 v[56:59], v[172:175], v[196:199], 0
	v_mfma_f32_16x16x32_bf16 v[44:47], v[156:159], v[204:207], 0
	v_mfma_f32_16x16x32_bf16 v[40:43], v[172:175], v[204:207], 0
	v_mfma_f32_16x16x32_bf16 v[28:31], v[156:159], v[212:215], 0
	v_mfma_f32_16x16x32_bf16 v[24:27], v[172:175], v[212:215], 0
	v_mfma_f32_16x16x32_bf16 v[12:15], v[156:159], v[220:223], 0
	v_mfma_f32_16x16x32_bf16 v[8:11], v[172:175], v[220:223], 0
	v_mfma_f32_16x16x32_bf16 v[60:63], v[168:171], v[200:203], v[60:63]
	v_mfma_f32_16x16x32_bf16 v[56:59], v[176:179], v[200:203], v[56:59]
	v_mfma_f32_16x16x32_bf16 v[44:47], v[168:171], v[208:211], v[44:47]
	v_mfma_f32_16x16x32_bf16 v[40:43], v[176:179], v[208:211], v[40:43]
	v_mfma_f32_16x16x32_bf16 v[28:31], v[168:171], v[216:219], v[28:31]
	v_mfma_f32_16x16x32_bf16 v[24:27], v[176:179], v[216:219], v[24:27]
	v_mfma_f32_16x16x32_bf16 v[12:15], v[168:171], v[224:227], v[12:15]
	v_mfma_f32_16x16x32_bf16 v[8:11], v[176:179], v[224:227], v[8:11]
	s_setprio 0
	s_setprio 1
	v_mfma_f32_16x16x32_bf16 v[52:55], v[180:183], v[196:199], 0
	v_mfma_f32_16x16x32_bf16 v[48:51], v[188:191], v[196:199], 0
	v_mfma_f32_16x16x32_bf16 v[36:39], v[180:183], v[204:207], 0
	v_mfma_f32_16x16x32_bf16 v[32:35], v[188:191], v[204:207], 0
	v_mfma_f32_16x16x32_bf16 v[20:23], v[180:183], v[212:215], 0
	v_mfma_f32_16x16x32_bf16 v[16:19], v[188:191], v[212:215], 0
	v_mfma_f32_16x16x32_bf16 v[4:7], v[180:183], v[220:223], 0
	v_mfma_f32_16x16x32_bf16 v[0:3], v[188:191], v[220:223], 0
	v_mfma_f32_16x16x32_bf16 v[52:55], v[184:187], v[200:203], v[52:55]
	v_mfma_f32_16x16x32_bf16 v[48:51], v[192:195], v[200:203], v[48:51]
	v_mfma_f32_16x16x32_bf16 v[36:39], v[184:187], v[208:211], v[36:39]
	v_mfma_f32_16x16x32_bf16 v[32:35], v[192:195], v[208:211], v[32:35]
	v_mfma_f32_16x16x32_bf16 v[20:23], v[184:187], v[216:219], v[20:23]
	v_mfma_f32_16x16x32_bf16 v[16:19], v[192:195], v[216:219], v[16:19]
	v_mfma_f32_16x16x32_bf16 v[4:7], v[184:187], v[224:227], v[4:7]
	v_mfma_f32_16x16x32_bf16 v[0:3], v[192:195], v[224:227], v[0:3]
	s_setprio 0
	s_barrier
	s_add_i32 s11, 0, 0x18000
	s_add_i32 s16, 0, 0x1c000
	v_add_u32_e32 v176, s11, v161
	v_add_u32_e32 v192, s16, v161
	ds_read_b128 v[156:159], v176
	ds_read_b128 v[168:171], v176 offset:1024
	ds_read_b128 v[172:175], v176 offset:2048
	ds_read_b128 v[176:179], v176 offset:3072
	ds_read_b128 v[180:183], v192
	ds_read_b128 v[184:187], v192 offset:1024
	ds_read_b128 v[188:191], v192 offset:2048
	ds_read_b128 v[192:195], v192 offset:3072
	s_add_u32 s14, s52, 0x40000
	s_addc_u32 s15, s53, 0
	s_mov_b32 m0, s60
	v_lshl_add_u64 v[236:237], s[14:15], 0, v[134:135]
	ds_read_b128 v[196:199], v164 offset:32768
	ds_read_b128 v[200:203], v164 offset:33792
	ds_read_b128 v[204:207], v164 offset:34816
	ds_read_b128 v[208:211], v164 offset:35840
	ds_read_b128 v[212:215], v164 offset:36864
	ds_read_b128 v[216:219], v164 offset:37888
	ds_read_b128 v[220:223], v164 offset:38912
	ds_read_b128 v[224:227], v164 offset:39936
	global_load_lds_dwordx4 v[236:237], off
	v_lshl_add_u64 v[236:237], s[14:15], 0, v[130:131]
	s_mov_b32 m0, s61
	s_nop 0
	global_load_lds_dwordx4 v[236:237], off
	s_waitcnt vmcnt(8)
	s_waitcnt lgkmcnt(0)
	s_barrier
	s_setprio 1
	s_waitcnt lgkmcnt(0)
	v_mfma_f32_16x16x32_bf16 v[124:127], v[156:159], v[196:199], v[124:127]
	v_mfma_f32_16x16x32_bf16 v[120:123], v[172:175], v[196:199], v[120:123]
	v_mfma_f32_16x16x32_bf16 v[108:111], v[156:159], v[204:207], v[108:111]
	v_mfma_f32_16x16x32_bf16 v[104:107], v[172:175], v[204:207], v[104:107]
	v_mfma_f32_16x16x32_bf16 v[92:95], v[156:159], v[212:215], v[92:95]
	v_mfma_f32_16x16x32_bf16 v[88:91], v[172:175], v[212:215], v[88:91]
	v_mfma_f32_16x16x32_bf16 v[76:79], v[156:159], v[220:223], v[76:79]
	v_mfma_f32_16x16x32_bf16 v[72:75], v[172:175], v[220:223], v[72:75]
	v_mfma_f32_16x16x32_bf16 v[124:127], v[168:171], v[200:203], v[124:127]
	v_mfma_f32_16x16x32_bf16 v[120:123], v[176:179], v[200:203], v[120:123]
	v_mfma_f32_16x16x32_bf16 v[108:111], v[168:171], v[208:211], v[108:111]
	v_mfma_f32_16x16x32_bf16 v[104:107], v[176:179], v[208:211], v[104:107]
	v_mfma_f32_16x16x32_bf16 v[92:95], v[168:171], v[216:219], v[92:95]
	v_mfma_f32_16x16x32_bf16 v[88:91], v[176:179], v[216:219], v[88:91]
	v_mfma_f32_16x16x32_bf16 v[76:79], v[168:171], v[224:227], v[76:79]
	v_mfma_f32_16x16x32_bf16 v[72:75], v[176:179], v[224:227], v[72:75]
	s_setprio 0
	s_setprio 1
	v_mfma_f32_16x16x32_bf16 v[116:119], v[180:183], v[196:199], v[116:119]
	v_mfma_f32_16x16x32_bf16 v[112:115], v[188:191], v[196:199], v[112:115]
	v_mfma_f32_16x16x32_bf16 v[100:103], v[180:183], v[204:207], v[100:103]
	v_mfma_f32_16x16x32_bf16 v[96:99], v[188:191], v[204:207], v[96:99]
	v_mfma_f32_16x16x32_bf16 v[84:87], v[180:183], v[212:215], v[84:87]
	v_mfma_f32_16x16x32_bf16 v[80:83], v[188:191], v[212:215], v[80:83]
	v_mfma_f32_16x16x32_bf16 v[68:71], v[180:183], v[220:223], v[68:71]
	v_mfma_f32_16x16x32_bf16 v[64:67], v[188:191], v[220:223], v[64:67]
	v_mfma_f32_16x16x32_bf16 v[116:119], v[184:187], v[200:203], v[116:119]
	v_mfma_f32_16x16x32_bf16 v[112:115], v[192:195], v[200:203], v[112:115]
	v_mfma_f32_16x16x32_bf16 v[100:103], v[184:187], v[208:211], v[100:103]
	v_mfma_f32_16x16x32_bf16 v[96:99], v[192:195], v[208:211], v[96:99]
	v_mfma_f32_16x16x32_bf16 v[84:87], v[184:187], v[216:219], v[84:87]
	v_mfma_f32_16x16x32_bf16 v[80:83], v[192:195], v[216:219], v[80:83]
	v_mfma_f32_16x16x32_bf16 v[68:71], v[184:187], v[224:227], v[68:71]
	v_mfma_f32_16x16x32_bf16 v[64:67], v[192:195], v[224:227], v[64:67]
	s_setprio 0
	s_barrier
; #define PG8_STAGE(bufoff, gbase, voff) do { _Pragma("unroll") for (int _i = 0; _i < 2; ++_i) \
;         __builtin_amdgcn_global_load_lds((const unsigned*)((const char*)(gbase) + (voff)[_i]), (PG8_LAS unsigned*)(lds + (bufoff) + ldsw + _i * 8192), 16, 0, 0); } while (0)
; #define PG8_LDA(dst, b, h) do { _Pragma("unroll") for (int m = 0; m < 4; ++m) _Pragma("unroll") for (int k = 0; k < 2; ++k) dst[m][k] = *(const PG8_LAS bf16x8*)(lds + PG8_SA(b, h) + aoff + m * 2048 + k * 1024); } while (0)
; #define PG8_MMA(ai, bj, At, Bt) do { __builtin_amdgcn_s_setprio(1); _Pragma("unroll") for (int m = 0; m < 4; ++m) _Pragma("unroll") for (int n = 0; n < 2; ++n) _Pragma("unroll") for (int k = 0; k < 2; ++k) \
;         acc[ai][bj][m][n] = __builtin_amdgcn_mfma_f32_16x16x32_bf16(Bt[n][k], At[m][k], acc[ai][bj][m][n], 0, 0, 0); __builtin_amdgcn_s_setprio(0); } while (0)
; #define PG8_WAIT_V(n) asm volatile("s_waitcnt vmcnt(" #n ")" ::: "memory")
; #define PG8_WAIT_L(n) asm volatile("s_waitcnt lgkmcnt(" #n ")" ::: "memory")
; #define PG8_BAR __builtin_amdgcn_s_barrier()
; #define PG8_SCHED __builtin_amdgcn_sched_barrier(0)
; template <class Epi, class Sched, bool ALIGN_EPI = false, bool SP2 = false, bool ABLK = false>
; __device__ __forceinline__ void gemm_phase(PG8_LAS unsigned char* lds, const Gemm g, const Sched& S, const Epi& E) {
;     ...
;         for (int t = 0; t < nt; t += 2) {
;     ...
;             PG8_LDA(At, 1, 1); PG8_STAGE(PG8_SB(1, 0), b3, voffB); PG8_STAGE(PG8_SB(1, 1), b3 + hstep, voffB); PG8_STAGE(PG8_SA(1, 0), a3, voffA);
;             PG8_WAIT_V(8); PG8_WAIT_L(0); PG8_BAR; PG8_MMA(1, 0, At, B0); PG8_MMA(1, 1, At, B1); PG8_BAR; PG8_SCHED;
	s_add_i32 s11, s11, s54
	v_lshl_add_u64 v[228:229], v[228:229], 0, s[30:31]
	s_mov_b32 m0, s11
	ds_read_b128 v[196:199], v164 offset:49152
	ds_read_b128 v[200:203], v164 offset:50176
	ds_read_b128 v[204:207], v164 offset:51200
	ds_read_b128 v[208:211], v164 offset:52224
	ds_read_b128 v[212:215], v164 offset:53248
	ds_read_b128 v[216:219], v164 offset:54272
	ds_read_b128 v[220:223], v164 offset:55296
	ds_read_b128 v[224:227], v164 offset:56320
	global_load_lds_dwordx4 v[228:229], off
	s_add_i32 m0, s11, 0x2000
	s_add_u32 s14, s50, 0x40080
	v_lshl_add_u64 v[228:229], v[230:231], 0, s[30:31]
	s_addc_u32 s15, s51, 0
	s_add_i32 s11, s16, s54
	global_load_lds_dwordx4 v[228:229], off
	v_lshl_add_u64 v[228:229], s[14:15], 0, v[132:133]
	s_mov_b32 m0, s11
	s_nop 0
	global_load_lds_dwordx4 v[228:229], off
	v_lshl_add_u64 v[228:229], s[14:15], 0, v[128:129]
	s_add_i32 m0, s11, 0x2000
	s_nop 0
	global_load_lds_dwordx4 v[228:229], off
	v_lshl_add_u64 v[228:229], v[232:233], 0, s[30:31]
	s_mov_b32 m0, s68
	s_nop 0
	global_load_lds_dwordx4 v[228:229], off
	v_lshl_add_u64 v[228:229], v[234:235], 0, s[30:31]
	s_mov_b32 m0, s69
	s_nop 0
	global_load_lds_dwordx4 v[228:229], off
	s_waitcnt vmcnt(8)
	s_waitcnt lgkmcnt(0)
	s_barrier
	s_setprio 1
	s_waitcnt lgkmcnt(0)
	v_mfma_f32_16x16x32_bf16 v[60:63], v[156:159], v[196:199], v[60:63]
	v_mfma_f32_16x16x32_bf16 v[56:59], v[172:175], v[196:199], v[56:59]
	v_mfma_f32_16x16x32_bf16 v[44:47], v[156:159], v[204:207], v[44:47]
	v_mfma_f32_16x16x32_bf16 v[40:43], v[172:175], v[204:207], v[40:43]
	v_mfma_f32_16x16x32_bf16 v[28:31], v[156:159], v[212:215], v[28:31]
	v_mfma_f32_16x16x32_bf16 v[24:27], v[172:175], v[212:215], v[24:27]
	v_mfma_f32_16x16x32_bf16 v[12:15], v[156:159], v[220:223], v[12:15]
	v_mfma_f32_16x16x32_bf16 v[8:11], v[172:175], v[220:223], v[8:11]
	v_mfma_f32_16x16x32_bf16 v[60:63], v[168:171], v[200:203], v[60:63]
	v_mfma_f32_16x16x32_bf16 v[56:59], v[176:179], v[200:203], v[56:59]
	v_mfma_f32_16x16x32_bf16 v[44:47], v[168:171], v[208:211], v[44:47]
	v_mfma_f32_16x16x32_bf16 v[40:43], v[176:179], v[208:211], v[40:43]
	v_mfma_f32_16x16x32_bf16 v[28:31], v[168:171], v[216:219], v[28:31]
	v_mfma_f32_16x16x32_bf16 v[24:27], v[176:179], v[216:219], v[24:27]
	v_mfma_f32_16x16x32_bf16 v[12:15], v[168:171], v[224:227], v[12:15]
	v_mfma_f32_16x16x32_bf16 v[8:11], v[176:179], v[224:227], v[8:11]
	s_setprio 0
	s_setprio 1
	v_mfma_f32_16x16x32_bf16 v[52:55], v[180:183], v[196:199], v[52:55]
	v_mfma_f32_16x16x32_bf16 v[48:51], v[188:191], v[196:199], v[48:51]
	v_mfma_f32_16x16x32_bf16 v[36:39], v[180:183], v[204:207], v[36:39]
	v_mfma_f32_16x16x32_bf16 v[32:35], v[188:191], v[204:207], v[32:35]
	v_mfma_f32_16x16x32_bf16 v[20:23], v[180:183], v[212:215], v[20:23]
	v_mfma_f32_16x16x32_bf16 v[16:19], v[188:191], v[212:215], v[16:19]
	v_mfma_f32_16x16x32_bf16 v[4:7], v[180:183], v[220:223], v[4:7]
	v_mfma_f32_16x16x32_bf16 v[0:3], v[188:191], v[220:223], v[0:3]
	v_mfma_f32_16x16x32_bf16 v[52:55], v[184:187], v[200:203], v[52:55]
	v_mfma_f32_16x16x32_bf16 v[48:51], v[192:195], v[200:203], v[48:51]
	v_mfma_f32_16x16x32_bf16 v[36:39], v[184:187], v[208:211], v[36:39]
	v_mfma_f32_16x16x32_bf16 v[32:35], v[192:195], v[208:211], v[32:35]
	v_mfma_f32_16x16x32_bf16 v[20:23], v[184:187], v[216:219], v[20:23]
	v_mfma_f32_16x16x32_bf16 v[16:19], v[192:195], v[216:219], v[16:19]
	v_mfma_f32_16x16x32_bf16 v[4:7], v[184:187], v[224:227], v[4:7]
	v_mfma_f32_16x16x32_bf16 v[0:3], v[192:195], v[224:227], v[0:3]
	s_setprio 0
	s_barrier
	s_add_i32 s10, s10, 2
	s_add_u32 s36, s36, 0x100
	s_addc_u32 s37, s37, 0
	s_add_u32 s8, s8, 0x100
	s_addc_u32 s9, s9, 0
	s_cmp_gt_u32 s10, 13
	s_cbranch_scc1 .Lpeel_post_3

; __device__ __forceinline__ float silu_f(float g) { return g * __builtin_amdgcn_rcpf(1.f + __builtin_amdgcn_exp2f(-1.4426950408889634f * g)); }
; __device__ __forceinline__ u32x4 pack8(f32x4 a, f32x4 b) { u32x4 o; o.x = cvt_pk(a.x, a.y); o.y = cvt_pk(a.z, a.w); o.z = cvt_pk(b.x, b.y); o.w = cvt_pk(b.z, b.w); return o; }
; __device__ __forceinline__ float rstd_of(const float* SS, int row, float invw) { return 1.0f / sqrtf(SS[row] * invw + EPS); }
;     __device__ __forceinline__ void operator()(const f32x4 (&acc)[2][2][4][2], const pg8::Unit& u, int wr, int wc, int fr, int fq) const {
;         const int row0 = u.pm * 256 + wr * 64 + fr, col0 = u.pn * 128 + wc * 32 + 8 * fq;
;         bf16_t* hb = H + (size_t)u.pm * 256 * FF + (size_t)(col0 >> 6) * (256 * 64) + (col0 & 63);
; #pragma unroll
;         for (int ai = 0; ai < 2; ++ai)
; #pragma unroll
;             for (int m = 0; m < 4; ++m) {
;                 const int row = row0 + ai * 128 + m * 16;
;                 const float r = SCALE ? rstd_of(SS, row, 1.f / 1024.f) : 1.f;
;                 const f32x4 g0 = acc[ai][0][m][0] * r, g1 = acc[ai][0][m][1] * r, u0 = acc[ai][1][m][0] * r, u1 = acc[ai][1][m][1] * r;
;                 f32x4 h0, h1;
;                 h0.x = silu_f(g0.x) * u0.x; h0.y = silu_f(g0.y) * u0.y; h0.z = silu_f(g0.z) * u0.z; h0.w = silu_f(g0.w) * u0.w;
;                 h1.x = silu_f(g1.x) * u1.x; h1.y = silu_f(g1.y) * u1.y; h1.z = silu_f(g1.z) * u1.z; h1.w = silu_f(g1.w) * u1.w;
;                 *(u32x4*)(hb + (wr * 64 + fr + ai * 128 + m * 16) * 64) = pack8(h0, h1);
.LBB0_827:
	v_mov_b32_e32 v200, v238
	v_mov_b32_e32 v201, v239
	v_mov_b32_e32 v202, v240
	v_mov_b32_e32 v203, v241
	v_mov_b32_e32 v204, v242
	v_mov_b32_e32 v205, v243
	v_mov_b32_e32 v206, v244
	v_mov_b32_e32 v207, v245
	s_lshl_b32 s1, s1, 7
	s_or_b32 s1, s1, s67
	s_mul_hi_i32 s4, s0, 0x160000
	s_mul_i32 s0, s0, 0x160000
	s_add_u32 s5, s64, s0
	s_addc_u32 s4, s65, s4
	s_ashr_i32 s0, s1, 6
	s_ashr_i32 s1, s0, 31
	s_lshl_b64 s[0:1], s[0:1], 15
	s_add_u32 s0, s5, s0
	s_addc_u32 s1, s4, s1
	v_lshl_add_u64 v[156:157], s[0:1], 0, v[136:137]
	v_mov_b32_e32 v208, 0xbfb8aa3b
	v_mov_b32_e32 v209, 0xbfb8aa3b
	v_mov_b32_e32 v210, 1.0
	v_mov_b32_e32 v211, 1.0
	s_movk_i32 s0, 0x1000
	v_lshl_add_u64 v[212:213], v[138:139], 1, v[156:157]
	v_add_co_u32_e32 v214, vcc, s0, v212
	v_addc_co_u32_e32 v215, vcc, 0, v213, vcc
	v_lshl_add_u64 v[216:217], v[140:141], 1, v[156:157]
	v_lshl_add_u64 v[218:219], v[142:143], 1, v[156:157]
	v_lshl_add_u64 v[220:221], v[144:145], 1, v[156:157]
	v_lshl_add_u64 v[222:223], v[146:147], 1, v[156:157]
	v_fmamk_f32 v200, v200, 0x3a800000, v165
	v_fmamk_f32 v201, v201, 0x3a800000, v165
	v_fmamk_f32 v202, v202, 0x3a800000, v165
	v_fmamk_f32 v203, v203, 0x3a800000, v165
	v_fmamk_f32 v204, v204, 0x3a800000, v165
	v_fmamk_f32 v205, v205, 0x3a800000, v165
	v_fmamk_f32 v206, v206, 0x3a800000, v165
	v_fmamk_f32 v207, v207, 0x3a800000, v165
	v_rsq_f32_e32 v200, v200
	v_rsq_f32_e32 v201, v201
	v_rsq_f32_e32 v202, v202
	v_rsq_f32_e32 v203, v203
	v_rsq_f32_e32 v204, v204
	v_rsq_f32_e32 v205, v205
	v_rsq_f32_e32 v206, v206
	v_rsq_f32_e32 v207, v207
	v_pk_mul_f32 v[124:125], v[124:125], v[200:201] op_sel_hi:[1,0]
	v_pk_mul_f32 v[126:127], v[126:127], v[200:201] op_sel_hi:[1,0]
	v_pk_mul_f32 v[120:121], v[120:121], v[200:201] op_sel_hi:[1,0]
	v_pk_mul_f32 v[122:123], v[122:123], v[200:201] op_sel_hi:[1,0]
	v_pk_mul_f32 v[116:117], v[116:117], v[200:201] op_sel_hi:[1,0]
	v_pk_mul_f32 v[118:119], v[118:119], v[200:201] op_sel_hi:[1,0]
	v_pk_mul_f32 v[112:113], v[112:113], v[200:201] op_sel_hi:[1,0]
	v_pk_mul_f32 v[114:115], v[114:115], v[200:201] op_sel_hi:[1,0]
	v_pk_mul_f32 v[168:169], v[124:125], v[208:209]
	v_pk_mul_f32 v[170:171], v[126:127], v[208:209]
	v_pk_mul_f32 v[172:173], v[120:121], v[208:209]
	v_pk_mul_f32 v[174:175], v[122:123], v[208:209]
	v_exp_f32_e32 v168, v168
	v_exp_f32_e32 v169, v169
	v_exp_f32_e32 v170, v170
	v_exp_f32_e32 v171, v171
	v_exp_f32_e32 v172, v172
	v_exp_f32_e32 v173, v173
	v_exp_f32_e32 v174, v174
	v_exp_f32_e32 v175, v175
	v_pk_add_f32 v[168:169], v[168:169], v[210:211]
	v_pk_add_f32 v[170:171], v[170:171], v[210:211]
	v_pk_add_f32 v[172:173], v[172:173], v[210:211]
	v_pk_add_f32 v[174:175], v[174:175], v[210:211]
	v_rcp_f32_e32 v168, v168
	v_rcp_f32_e32 v169, v169
	v_rcp_f32_e32 v170, v170
	v_rcp_f32_e32 v171, v171
	v_rcp_f32_e32 v172, v172
	v_rcp_f32_e32 v173, v173
	v_rcp_f32_e32 v174, v174
	v_rcp_f32_e32 v175, v175
	v_pk_mul_f32 v[168:169], v[124:125], v[168:169]
	v_pk_mul_f32 v[170:171], v[126:127], v[170:171]
	v_pk_mul_f32 v[172:173], v[120:121], v[172:173]
	v_pk_mul_f32 v[174:175], v[122:123], v[174:175]
	v_pk_mul_f32 v[168:169], v[116:117], v[168:169]
	v_pk_mul_f32 v[170:171], v[118:119], v[170:171]
	v_pk_mul_f32 v[172:173], v[112:113], v[172:173]
	v_pk_mul_f32 v[174:175], v[114:115], v[174:175]
	v_cvt_pk_bf16_f32 v112, v168, v169
	v_cvt_pk_bf16_f32 v113, v170, v171
	v_cvt_pk_bf16_f32 v114, v172, v173
	v_cvt_pk_bf16_f32 v115, v174, v175
	global_store_dwordx4 v[212:213], v[112:115], off
	v_pk_mul_f32 v[108:109], v[108:109], v[200:201] op_sel:[0,1] op_sel_hi:[1,1]
	v_pk_mul_f32 v[110:111], v[110:111], v[200:201] op_sel:[0,1] op_sel_hi:[1,1]
	v_pk_mul_f32 v[104:105], v[104:105], v[200:201] op_sel:[0,1] op_sel_hi:[1,1]
	v_pk_mul_f32 v[106:107], v[106:107], v[200:201] op_sel:[0,1] op_sel_hi:[1,1]
	v_pk_mul_f32 v[100:101], v[100:101], v[200:201] op_sel:[0,1] op_sel_hi:[1,1]
	v_pk_mul_f32 v[102:103], v[102:103], v[200:201] op_sel:[0,1] op_sel_hi:[1,1]
	v_pk_mul_f32 v[96:97], v[96:97], v[200:201] op_sel:[0,1] op_sel_hi:[1,1]
	v_pk_mul_f32 v[98:99], v[98:99], v[200:201] op_sel:[0,1] op_sel_hi:[1,1]
	v_pk_mul_f32 v[176:177], v[108:109], v[208:209]
	v_pk_mul_f32 v[178:179], v[110:111], v[208:209]
	v_pk_mul_f32 v[180:181], v[104:105], v[208:209]
	v_pk_mul_f32 v[182:183], v[106:107], v[208:209]
	v_exp_f32_e32 v176, v176
	v_exp_f32_e32 v177, v177
	v_exp_f32_e32 v178, v178
	v_exp_f32_e32 v179, v179
	v_exp_f32_e32 v180, v180
	v_exp_f32_e32 v181, v181
	v_exp_f32_e32 v182, v182
	v_exp_f32_e32 v183, v183
	v_pk_add_f32 v[176:177], v[176:177], v[210:211]
	v_pk_add_f32 v[178:179], v[178:179], v[210:211]
	v_pk_add_f32 v[180:181], v[180:181], v[210:211]
	v_pk_add_f32 v[182:183], v[182:183], v[210:211]
	v_rcp_f32_e32 v176, v176
	v_rcp_f32_e32 v177, v177
	v_rcp_f32_e32 v178, v178
	v_rcp_f32_e32 v179, v179
	v_rcp_f32_e32 v180, v180
	v_rcp_f32_e32 v181, v181
	v_rcp_f32_e32 v182, v182
	v_rcp_f32_e32 v183, v183
	v_pk_mul_f32 v[176:177], v[108:109], v[176:177]
	v_pk_mul_f32 v[178:179], v[110:111], v[178:179]
	v_pk_mul_f32 v[180:181], v[104:105], v[180:181]
	v_pk_mul_f32 v[182:183], v[106:107], v[182:183]
	v_pk_mul_f32 v[176:177], v[100:101], v[176:177]
	v_pk_mul_f32 v[178:179], v[102:103], v[178:179]
	v_pk_mul_f32 v[180:181], v[96:97], v[180:181]
	v_pk_mul_f32 v[182:183], v[98:99], v[182:183]
	v_cvt_pk_bf16_f32 v96, v176, v177
	v_cvt_pk_bf16_f32 v97, v178, v179
	v_cvt_pk_bf16_f32 v98, v180, v181
	v_cvt_pk_bf16_f32 v99, v182, v183
	global_store_dwordx4 v[212:213], v[96:99], off offset:2048
	v_pk_mul_f32 v[92:93], v[92:93], v[202:203] op_sel_hi:[1,0]
	v_pk_mul_f32 v[94:95], v[94:95], v[202:203] op_sel_hi:[1,0]
; __device__ __forceinline__ float silu_f(float g) { return g * __builtin_amdgcn_rcpf(1.f + __builtin_amdgcn_exp2f(-1.4426950408889634f * g)); }
; __device__ __forceinline__ u32x4 pack8(f32x4 a, f32x4 b) { u32x4 o; o.x = cvt_pk(a.x, a.y); o.y = cvt_pk(a.z, a.w); o.z = cvt_pk(b.x, b.y); o.w = cvt_pk(b.z, b.w); return o; }
; __device__ __forceinline__ float rstd_of(const float* SS, int row, float invw) { return 1.0f / sqrtf(SS[row] * invw + EPS); }
;     __device__ __forceinline__ void operator()(const f32x4 (&acc)[2][2][4][2], const pg8::Unit& u, int wr, int wc, int fr, int fq) const {
;     ...
;                 const int row = row0 + ai * 128 + m * 16;
;                 const float r = SCALE ? rstd_of(SS, row, 1.f / 1024.f) : 1.f;
;                 const f32x4 g0 = acc[ai][0][m][0] * r, g1 = acc[ai][0][m][1] * r, u0 = acc[ai][1][m][0] * r, u1 = acc[ai][1][m][1] * r;
;                 f32x4 h0, h1;
;                 h0.x = silu_f(g0.x) * u0.x; h0.y = silu_f(g0.y) * u0.y; h0.z = silu_f(g0.z) * u0.z; h0.w = silu_f(g0.w) * u0.w;
;                 h1.x = silu_f(g1.x) * u1.x; h1.y = silu_f(g1.y) * u1.y; h1.z = silu_f(g1.z) * u1.z; h1.w = silu_f(g1.w) * u1.w;
;                 *(u32x4*)(hb + (wr * 64 + fr + ai * 128 + m * 16) * 64) = pack8(h0, h1);
	v_pk_mul_f32 v[88:89], v[88:89], v[202:203] op_sel_hi:[1,0]
	v_pk_mul_f32 v[90:91], v[90:91], v[202:203] op_sel_hi:[1,0]
	v_pk_mul_f32 v[84:85], v[84:85], v[202:203] op_sel_hi:[1,0]
	v_pk_mul_f32 v[86:87], v[86:87], v[202:203] op_sel_hi:[1,0]
	v_pk_mul_f32 v[80:81], v[80:81], v[202:203] op_sel_hi:[1,0]
	v_pk_mul_f32 v[82:83], v[82:83], v[202:203] op_sel_hi:[1,0]
	v_pk_mul_f32 v[168:169], v[92:93], v[208:209]
	v_pk_mul_f32 v[170:171], v[94:95], v[208:209]
	v_pk_mul_f32 v[172:173], v[88:89], v[208:209]
	v_pk_mul_f32 v[174:175], v[90:91], v[208:209]
	v_exp_f32_e32 v168, v168
	v_exp_f32_e32 v169, v169
	v_exp_f32_e32 v170, v170
	v_exp_f32_e32 v171, v171
	v_exp_f32_e32 v172, v172
	v_exp_f32_e32 v173, v173
	v_exp_f32_e32 v174, v174
	v_exp_f32_e32 v175, v175
	v_pk_add_f32 v[168:169], v[168:169], v[210:211]
	v_pk_add_f32 v[170:171], v[170:171], v[210:211]
	v_pk_add_f32 v[172:173], v[172:173], v[210:211]
	v_pk_add_f32 v[174:175], v[174:175], v[210:211]
	v_rcp_f32_e32 v168, v168
	v_rcp_f32_e32 v169, v169
	v_rcp_f32_e32 v170, v170
	v_rcp_f32_e32 v171, v171
	v_rcp_f32_e32 v172, v172
	v_rcp_f32_e32 v173, v173
	v_rcp_f32_e32 v174, v174
	v_rcp_f32_e32 v175, v175
	v_pk_mul_f32 v[168:169], v[92:93], v[168:169]
	v_pk_mul_f32 v[170:171], v[94:95], v[170:171]
	v_pk_mul_f32 v[172:173], v[88:89], v[172:173]
	v_pk_mul_f32 v[174:175], v[90:91], v[174:175]
	v_pk_mul_f32 v[168:169], v[84:85], v[168:169]
	v_pk_mul_f32 v[170:171], v[86:87], v[170:171]
	v_pk_mul_f32 v[172:173], v[80:81], v[172:173]
	v_pk_mul_f32 v[174:175], v[82:83], v[174:175]
	v_cvt_pk_bf16_f32 v80, v168, v169
	v_cvt_pk_bf16_f32 v81, v170, v171
	v_cvt_pk_bf16_f32 v82, v172, v173
	v_cvt_pk_bf16_f32 v83, v174, v175
	global_store_dwordx4 v[214:215], v[80:83], off
	v_pk_mul_f32 v[76:77], v[76:77], v[202:203] op_sel:[0,1] op_sel_hi:[1,1]
	v_pk_mul_f32 v[78:79], v[78:79], v[202:203] op_sel:[0,1] op_sel_hi:[1,1]
	v_pk_mul_f32 v[72:73], v[72:73], v[202:203] op_sel:[0,1] op_sel_hi:[1,1]
	v_pk_mul_f32 v[74:75], v[74:75], v[202:203] op_sel:[0,1] op_sel_hi:[1,1]
	v_pk_mul_f32 v[68:69], v[68:69], v[202:203] op_sel:[0,1] op_sel_hi:[1,1]
	v_pk_mul_f32 v[70:71], v[70:71], v[202:203] op_sel:[0,1] op_sel_hi:[1,1]
	v_pk_mul_f32 v[64:65], v[64:65], v[202:203] op_sel:[0,1] op_sel_hi:[1,1]
	v_pk_mul_f32 v[66:67], v[66:67], v[202:203] op_sel:[0,1] op_sel_hi:[1,1]
	v_pk_mul_f32 v[176:177], v[76:77], v[208:209]
	v_pk_mul_f32 v[178:179], v[78:79], v[208:209]
	v_pk_mul_f32 v[180:181], v[72:73], v[208:209]
	v_pk_mul_f32 v[182:183], v[74:75], v[208:209]
	v_exp_f32_e32 v176, v176
	v_exp_f32_e32 v177, v177
	v_exp_f32_e32 v178, v178
	v_exp_f32_e32 v179, v179
	v_exp_f32_e32 v180, v180
	v_exp_f32_e32 v181, v181
	v_exp_f32_e32 v182, v182
	v_exp_f32_e32 v183, v183
	v_pk_add_f32 v[176:177], v[176:177], v[210:211]
	v_pk_add_f32 v[178:179], v[178:179], v[210:211]
	v_pk_add_f32 v[180:181], v[180:181], v[210:211]
	v_pk_add_f32 v[182:183], v[182:183], v[210:211]
	v_rcp_f32_e32 v176, v176
	v_rcp_f32_e32 v177, v177
	v_rcp_f32_e32 v178, v178
	v_rcp_f32_e32 v179, v179
	v_rcp_f32_e32 v180, v180
	v_rcp_f32_e32 v181, v181
	v_rcp_f32_e32 v182, v182
	v_rcp_f32_e32 v183, v183
	v_pk_mul_f32 v[176:177], v[76:77], v[176:177]
	v_pk_mul_f32 v[178:179], v[78:79], v[178:179]
	v_pk_mul_f32 v[180:181], v[72:73], v[180:181]
	v_pk_mul_f32 v[182:183], v[74:75], v[182:183]
	v_pk_mul_f32 v[176:177], v[68:69], v[176:177]
	v_pk_mul_f32 v[178:179], v[70:71], v[178:179]
	v_pk_mul_f32 v[180:181], v[64:65], v[180:181]
	v_pk_mul_f32 v[182:183], v[66:67], v[182:183]
	v_cvt_pk_bf16_f32 v64, v176, v177
	v_cvt_pk_bf16_f32 v65, v178, v179
	v_cvt_pk_bf16_f32 v66, v180, v181
	v_cvt_pk_bf16_f32 v67, v182, v183
	global_store_dwordx4 v[214:215], v[64:67], off offset:2048
	v_pk_mul_f32 v[60:61], v[60:61], v[204:205] op_sel_hi:[1,0]
	v_pk_mul_f32 v[62:63], v[62:63], v[204:205] op_sel_hi:[1,0]
	v_pk_mul_f32 v[56:57], v[56:57], v[204:205] op_sel_hi:[1,0]
	v_pk_mul_f32 v[58:59], v[58:59], v[204:205] op_sel_hi:[1,0]
	v_pk_mul_f32 v[52:53], v[52:53], v[204:205] op_sel_hi:[1,0]
	v_pk_mul_f32 v[54:55], v[54:55], v[204:205] op_sel_hi:[1,0]
	v_pk_mul_f32 v[48:49], v[48:49], v[204:205] op_sel_hi:[1,0]
	v_pk_mul_f32 v[50:51], v[50:51], v[204:205] op_sel_hi:[1,0]
	v_pk_mul_f32 v[168:169], v[60:61], v[208:209]
	v_pk_mul_f32 v[170:171], v[62:63], v[208:209]
	v_pk_mul_f32 v[172:173], v[56:57], v[208:209]
	v_pk_mul_f32 v[174:175], v[58:59], v[208:209]
	v_exp_f32_e32 v168, v168
	v_exp_f32_e32 v169, v169
	v_exp_f32_e32 v170, v170
	v_exp_f32_e32 v171, v171
	v_exp_f32_e32 v172, v172
	v_exp_f32_e32 v173, v173
	v_exp_f32_e32 v174, v174
	v_exp_f32_e32 v175, v175
	v_pk_add_f32 v[168:169], v[168:169], v[210:211]
	v_pk_add_f32 v[170:171], v[170:171], v[210:211]
	v_pk_add_f32 v[172:173], v[172:173], v[210:211]
	v_pk_add_f32 v[174:175], v[174:175], v[210:211]
	v_rcp_f32_e32 v168, v168
	v_rcp_f32_e32 v169, v169
	v_rcp_f32_e32 v170, v170
	v_rcp_f32_e32 v171, v171
	v_rcp_f32_e32 v172, v172
	v_rcp_f32_e32 v173, v173
	v_rcp_f32_e32 v174, v174
	v_rcp_f32_e32 v175, v175
	v_pk_mul_f32 v[168:169], v[60:61], v[168:169]
	v_pk_mul_f32 v[170:171], v[62:63], v[170:171]
	v_pk_mul_f32 v[172:173], v[56:57], v[172:173]
	v_pk_mul_f32 v[174:175], v[58:59], v[174:175]
	v_pk_mul_f32 v[168:169], v[52:53], v[168:169]
	v_pk_mul_f32 v[170:171], v[54:55], v[170:171]
	v_pk_mul_f32 v[172:173], v[48:49], v[172:173]
	v_pk_mul_f32 v[174:175], v[50:51], v[174:175]
	v_cvt_pk_bf16_f32 v48, v168, v169
	v_cvt_pk_bf16_f32 v49, v170, v171
	v_cvt_pk_bf16_f32 v50, v172, v173
	v_cvt_pk_bf16_f32 v51, v174, v175
	global_store_dwordx4 v[216:217], v[48:51], off
	v_pk_mul_f32 v[44:45], v[44:45], v[204:205] op_sel:[0,1] op_sel_hi:[1,1]
; #define PG8_BAR __builtin_amdgcn_s_barrier()
; __device__ __forceinline__ float silu_f(float g) { return g * __builtin_amdgcn_rcpf(1.f + __builtin_amdgcn_exp2f(-1.4426950408889634f * g)); }
; __device__ __forceinline__ u32x4 pack8(f32x4 a, f32x4 b) { u32x4 o; o.x = cvt_pk(a.x, a.y); o.y = cvt_pk(a.z, a.w); o.z = cvt_pk(b.x, b.y); o.w = cvt_pk(b.z, b.w); return o; }
; template <class Epi, class Sched, bool ALIGN_EPI = false, bool SP2 = false, bool ABLK = false>
; __device__ __forceinline__ void gemm_phase(PG8_LAS unsigned char* lds, const Gemm g, const Sched& S, const Epi& E) {
;     ...
;         if (!has_next) break;
; #pragma unroll
;         for (int a = 0; a < 2; ++a)
; #pragma unroll
;             for (int b = 0; b < 2; ++b)
; #pragma unroll
;                 for (int m = 0; m < 4; ++m)
; #pragma unroll
;                     for (int n = 0; n < 2; ++n) acc[a][b][m][n] = (f32x4){0.f, 0.f, 0.f, 0.f};
;         cur = nxt; cA = nA; cB = nB; ++ui;
;         if constexpr (ALIGN_EPI) { if (wr == 1) PG8_BAR; }
;     __device__ __forceinline__ void operator()(const f32x4 (&acc)[2][2][4][2], const pg8::Unit& u, int wr, int wc, int fr, int fq) const {
;     ...
;                 const f32x4 g0 = acc[ai][0][m][0] * r, g1 = acc[ai][0][m][1] * r, u0 = acc[ai][1][m][0] * r, u1 = acc[ai][1][m][1] * r;
;                 f32x4 h0, h1;
;                 h0.x = silu_f(g0.x) * u0.x; h0.y = silu_f(g0.y) * u0.y; h0.z = silu_f(g0.z) * u0.z; h0.w = silu_f(g0.w) * u0.w;
;                 h1.x = silu_f(g1.x) * u1.x; h1.y = silu_f(g1.y) * u1.y; h1.z = silu_f(g1.z) * u1.z; h1.w = silu_f(g1.w) * u1.w;
;                 *(u32x4*)(hb + (wr * 64 + fr + ai * 128 + m * 16) * 64) = pack8(h0, h1);
	v_pk_mul_f32 v[46:47], v[46:47], v[204:205] op_sel:[0,1] op_sel_hi:[1,1]
	v_pk_mul_f32 v[40:41], v[40:41], v[204:205] op_sel:[0,1] op_sel_hi:[1,1]
	v_pk_mul_f32 v[42:43], v[42:43], v[204:205] op_sel:[0,1] op_sel_hi:[1,1]
	v_pk_mul_f32 v[36:37], v[36:37], v[204:205] op_sel:[0,1] op_sel_hi:[1,1]
	v_pk_mul_f32 v[38:39], v[38:39], v[204:205] op_sel:[0,1] op_sel_hi:[1,1]
	v_pk_mul_f32 v[32:33], v[32:33], v[204:205] op_sel:[0,1] op_sel_hi:[1,1]
	v_pk_mul_f32 v[34:35], v[34:35], v[204:205] op_sel:[0,1] op_sel_hi:[1,1]
	v_pk_mul_f32 v[176:177], v[44:45], v[208:209]
	v_pk_mul_f32 v[178:179], v[46:47], v[208:209]
	v_pk_mul_f32 v[180:181], v[40:41], v[208:209]
	v_pk_mul_f32 v[182:183], v[42:43], v[208:209]
	v_exp_f32_e32 v176, v176
	v_exp_f32_e32 v177, v177
	v_exp_f32_e32 v178, v178
	v_exp_f32_e32 v179, v179
	v_exp_f32_e32 v180, v180
	v_exp_f32_e32 v181, v181
	v_exp_f32_e32 v182, v182
	v_exp_f32_e32 v183, v183
	v_pk_add_f32 v[176:177], v[176:177], v[210:211]
	v_pk_add_f32 v[178:179], v[178:179], v[210:211]
	v_pk_add_f32 v[180:181], v[180:181], v[210:211]
	v_pk_add_f32 v[182:183], v[182:183], v[210:211]
	v_rcp_f32_e32 v176, v176
	v_rcp_f32_e32 v177, v177
	v_rcp_f32_e32 v178, v178
	v_rcp_f32_e32 v179, v179
	v_rcp_f32_e32 v180, v180
	v_rcp_f32_e32 v181, v181
	v_rcp_f32_e32 v182, v182
	v_rcp_f32_e32 v183, v183
	v_pk_mul_f32 v[176:177], v[44:45], v[176:177]
	v_pk_mul_f32 v[178:179], v[46:47], v[178:179]
	v_pk_mul_f32 v[180:181], v[40:41], v[180:181]
	v_pk_mul_f32 v[182:183], v[42:43], v[182:183]
	v_pk_mul_f32 v[176:177], v[36:37], v[176:177]
	v_pk_mul_f32 v[178:179], v[38:39], v[178:179]
	v_pk_mul_f32 v[180:181], v[32:33], v[180:181]
	v_pk_mul_f32 v[182:183], v[34:35], v[182:183]
	v_cvt_pk_bf16_f32 v32, v176, v177
	v_cvt_pk_bf16_f32 v33, v178, v179
	v_cvt_pk_bf16_f32 v34, v180, v181
	v_cvt_pk_bf16_f32 v35, v182, v183
	global_store_dwordx4 v[218:219], v[32:35], off
	v_pk_mul_f32 v[28:29], v[28:29], v[206:207] op_sel_hi:[1,0]
	v_pk_mul_f32 v[30:31], v[30:31], v[206:207] op_sel_hi:[1,0]
	v_pk_mul_f32 v[24:25], v[24:25], v[206:207] op_sel_hi:[1,0]
	v_pk_mul_f32 v[26:27], v[26:27], v[206:207] op_sel_hi:[1,0]
	v_pk_mul_f32 v[20:21], v[20:21], v[206:207] op_sel_hi:[1,0]
	v_pk_mul_f32 v[22:23], v[22:23], v[206:207] op_sel_hi:[1,0]
	v_pk_mul_f32 v[16:17], v[16:17], v[206:207] op_sel_hi:[1,0]
	v_pk_mul_f32 v[18:19], v[18:19], v[206:207] op_sel_hi:[1,0]
	v_pk_mul_f32 v[168:169], v[28:29], v[208:209]
	v_pk_mul_f32 v[170:171], v[30:31], v[208:209]
	v_pk_mul_f32 v[172:173], v[24:25], v[208:209]
	v_pk_mul_f32 v[174:175], v[26:27], v[208:209]
	v_exp_f32_e32 v168, v168
	v_exp_f32_e32 v169, v169
	v_exp_f32_e32 v170, v170
	v_exp_f32_e32 v171, v171
	v_exp_f32_e32 v172, v172
	v_exp_f32_e32 v173, v173
	v_exp_f32_e32 v174, v174
	v_exp_f32_e32 v175, v175
	v_pk_add_f32 v[168:169], v[168:169], v[210:211]
	v_pk_add_f32 v[170:171], v[170:171], v[210:211]
	v_pk_add_f32 v[172:173], v[172:173], v[210:211]
	v_pk_add_f32 v[174:175], v[174:175], v[210:211]
	v_rcp_f32_e32 v168, v168
	v_rcp_f32_e32 v169, v169
	v_rcp_f32_e32 v170, v170
	v_rcp_f32_e32 v171, v171
	v_rcp_f32_e32 v172, v172
	v_rcp_f32_e32 v173, v173
	v_rcp_f32_e32 v174, v174
	v_rcp_f32_e32 v175, v175
	v_pk_mul_f32 v[168:169], v[28:29], v[168:169]
	v_pk_mul_f32 v[170:171], v[30:31], v[170:171]
	v_pk_mul_f32 v[172:173], v[24:25], v[172:173]
	v_pk_mul_f32 v[174:175], v[26:27], v[174:175]
	v_pk_mul_f32 v[168:169], v[20:21], v[168:169]
	v_pk_mul_f32 v[170:171], v[22:23], v[170:171]
	v_pk_mul_f32 v[172:173], v[16:17], v[172:173]
	v_pk_mul_f32 v[174:175], v[18:19], v[174:175]
	v_cvt_pk_bf16_f32 v16, v168, v169
	v_cvt_pk_bf16_f32 v17, v170, v171
	v_cvt_pk_bf16_f32 v18, v172, v173
	v_cvt_pk_bf16_f32 v19, v174, v175
	global_store_dwordx4 v[220:221], v[16:19], off
	v_pk_mul_f32 v[12:13], v[12:13], v[206:207] op_sel:[0,1] op_sel_hi:[1,1]
	v_pk_mul_f32 v[14:15], v[14:15], v[206:207] op_sel:[0,1] op_sel_hi:[1,1]
	v_pk_mul_f32 v[8:9], v[8:9], v[206:207] op_sel:[0,1] op_sel_hi:[1,1]
	v_pk_mul_f32 v[10:11], v[10:11], v[206:207] op_sel:[0,1] op_sel_hi:[1,1]
	v_pk_mul_f32 v[4:5], v[4:5], v[206:207] op_sel:[0,1] op_sel_hi:[1,1]
	v_pk_mul_f32 v[6:7], v[6:7], v[206:207] op_sel:[0,1] op_sel_hi:[1,1]
	v_pk_mul_f32 v[0:1], v[0:1], v[206:207] op_sel:[0,1] op_sel_hi:[1,1]
	v_pk_mul_f32 v[2:3], v[2:3], v[206:207] op_sel:[0,1] op_sel_hi:[1,1]
	v_pk_mul_f32 v[176:177], v[12:13], v[208:209]
	v_pk_mul_f32 v[178:179], v[14:15], v[208:209]
	v_pk_mul_f32 v[180:181], v[8:9], v[208:209]
	v_pk_mul_f32 v[182:183], v[10:11], v[208:209]
	v_exp_f32_e32 v176, v176
	v_exp_f32_e32 v177, v177
	v_exp_f32_e32 v178, v178
	v_exp_f32_e32 v179, v179
	v_exp_f32_e32 v180, v180
	v_exp_f32_e32 v181, v181
	v_exp_f32_e32 v182, v182
	v_exp_f32_e32 v183, v183
	v_pk_add_f32 v[176:177], v[176:177], v[210:211]
	v_pk_add_f32 v[178:179], v[178:179], v[210:211]
	v_pk_add_f32 v[180:181], v[180:181], v[210:211]
	v_pk_add_f32 v[182:183], v[182:183], v[210:211]
	v_rcp_f32_e32 v176, v176
	v_rcp_f32_e32 v177, v177
	v_rcp_f32_e32 v178, v178
	v_rcp_f32_e32 v179, v179
	v_rcp_f32_e32 v180, v180
	v_rcp_f32_e32 v181, v181
	v_rcp_f32_e32 v182, v182
	v_rcp_f32_e32 v183, v183
	v_pk_mul_f32 v[176:177], v[12:13], v[176:177]
	v_pk_mul_f32 v[178:179], v[14:15], v[178:179]
	v_pk_mul_f32 v[180:181], v[8:9], v[180:181]
	v_pk_mul_f32 v[182:183], v[10:11], v[182:183]
	v_pk_mul_f32 v[176:177], v[4:5], v[176:177]
	v_pk_mul_f32 v[178:179], v[6:7], v[178:179]
	v_pk_mul_f32 v[180:181], v[0:1], v[180:181]
	v_pk_mul_f32 v[182:183], v[2:3], v[182:183]
	v_cvt_pk_bf16_f32 v0, v176, v177
	v_cvt_pk_bf16_f32 v1, v178, v179
	v_cvt_pk_bf16_f32 v2, v180, v181
	v_cvt_pk_bf16_f32 v3, v182, v183
	global_store_dwordx4 v[222:223], v[0:3], off
	s_mov_b64 s[0:1], -1
	s_andn2_b64 vcc, exec, s[38:39]
	s_cbranch_vccnz .LBB0_820
	s_andn2_b64 vcc, exec, s[28:29]
	s_cbranch_vccnz .LBB0_819
	s_barrier
	s_branch .LBB0_819
